# S5 block loops: redundant zeroing of the (B u) MFMA A operand removed (B is zero for k >= 16), MFMAs read the prefetched rows directly
# baseline (speedup 1.0000x reference)
; #define LDS_WAIT() asm volatile("s_waitcnt lgkmcnt(0)" ::: "memory")
; #define MFMA16(a, b, c) __builtin_amdgcn_mfma_f32_16x16x32_bf16(a, b, c, 0, 0, 0)
; __device__ __forceinline__ void s5_phase(LAS unsigned char* lds, const bf16_t* USSM, const float* S5A, const float* S5B, const float* c_re, const float* c_im, const float* dskip,
;                                          bf16_t* YSSM, int tid, int lane, int wave) {
;     ...
;         for (int tb = 0; tb < 64; ++tb) {
;             bf16x8 a = *(const bf16x8*)(ub + (size_t)(tb * 16 + r16) * 1024 + (q4 & 1) * 8); if (q4 >= 2) a = zf;
; #pragma unroll
;             for (int nt = 0; nt < 8; ++nt) { const f32x4 acc = MFMA16(a, bfr[nt], z4);
; #pragma unroll
;                 for (int i = 0; i < 4; ++i) BU[(q4 * 4 + i) * 132 + nt * 16 + r16] = acc[i]; }
;             LDS_WAIT();
; #pragma unroll
;             for (int t = 0; t < 16; ++t) { const float br = BU[t * 132 + lane], bi = BU[t * 132 + 64 + lane];
;                 const float nr = are * xr - aim * xi + br, ni = are * xi + aim * xr + bi; xr = nr; xi = ni; }
;             LDS_WAIT();
;         }
;         carry[(wave * 64 + lane) * 2] = xr; carry[(wave * 64 + lane) * 2 + 1] = xi;
;         __syncthreads();
;         float pr = are, pi = aim;
; #pragma unroll
;         for (int k = 0; k < 10; ++k) { const float t2 = pr * pr - pi * pi; pi = 2.f * pr * pi; pr = t2; }
;         xr = 0.f; xi = 0.f;
;         for (int k = 0; k < wave; ++k) { const float er = carry[(k * 64 + lane) * 2], ei = carry[(k * 64 + lane) * 2 + 1]; const float nr = pr * xr - pi * xi + er, ni = pr * xi + pi * xr + ei; xr = nr; xi = ni; }
.LBB0_585:
	v_mov_b32_e32 v158, v48
	v_mov_b32_e32 v159, v49
	s_add_u32 s58, s58, 0x8000
	s_addc_u32 s59, s59, 0
	s_cmp_eq_u32 s58, 0x200000
	s_waitcnt vmcnt(0)
	s_nop 1
	v_mfma_f32_16x16x32_bf16 v[54:57], v[148:151], v[0:3], 0
	v_mfma_f32_16x16x32_bf16 v[58:61], v[148:151], v[4:7], 0
	v_mfma_f32_16x16x32_bf16 v[62:65], v[148:151], v[8:11], 0
	v_mfma_f32_16x16x32_bf16 v[66:69], v[148:151], v[16:19], 0
	v_mfma_f32_16x16x32_bf16 v[70:73], v[148:151], v[12:15], 0
	v_mfma_f32_16x16x32_bf16 v[74:77], v[148:151], v[20:23], 0
	v_mfma_f32_16x16x32_bf16 v[100:103], v[148:151], v[24:27], 0
	v_mfma_f32_16x16x32_bf16 v[48:51], v[148:151], v[28:31], 0
	v_lshl_add_u64 v[156:157], v[96:97], 0, s[58:59]
	global_load_dwordx4 v[148:151], v[156:157], off
	s_nop 1
	ds_write2_b32 v124, v54, v58 offset1:16
	ds_write2_b32 v124, v55, v59 offset0:132 offset1:148
	ds_write2_b32 v125, v56, v60 offset0:8 offset1:24
	ds_write2_b32 v125, v57, v61 offset0:140 offset1:156
	ds_write2_b32 v124, v62, v66 offset0:32 offset1:48
	ds_write2_b32 v124, v63, v67 offset0:164 offset1:180
	ds_write2_b32 v125, v64, v68 offset0:40 offset1:56
	ds_write2_b32 v125, v65, v69 offset0:172 offset1:188
	ds_write2_b32 v124, v70, v74 offset0:64 offset1:80
	ds_write2_b32 v124, v71, v75 offset0:196 offset1:212
	ds_write2_b32 v125, v72, v76 offset0:72 offset1:88
	ds_write2_b32 v125, v73, v77 offset0:204 offset1:220
	ds_write2_b32 v124, v100, v48 offset0:96 offset1:112
	ds_write2_b32 v124, v101, v49 offset0:228 offset1:244
	ds_write2_b32 v125, v102, v50 offset0:104 offset1:120
	ds_write2_b32 v125, v103, v51 offset0:236 offset1:252
	s_waitcnt lgkmcnt(0)
	ds_read2st64_b32 v[48:49], v111 offset0:16 offset1:17
	ds_read2st64_b32 v[50:51], v126 offset0:18 offset1:19
	ds_read2st64_b32 v[52:53], v127 offset0:20 offset1:21
	ds_read2st64_b32 v[54:55], v128 offset0:22 offset1:23
	ds_read2st64_b32 v[56:57], v129 offset0:24 offset1:25
	ds_read2st64_b32 v[58:59], v130 offset0:26 offset1:27
	ds_read2st64_b32 v[60:61], v131 offset0:28 offset1:29
	ds_read2st64_b32 v[62:63], v132 offset0:30 offset1:31
	ds_read2st64_b32 v[64:65], v133 offset0:32 offset1:33
	ds_read2st64_b32 v[66:67], v134 offset0:34 offset1:35
	ds_read2st64_b32 v[68:69], v135 offset0:36 offset1:37
	ds_read2st64_b32 v[70:71], v136 offset0:38 offset1:39
	ds_read2st64_b32 v[72:73], v137 offset0:40 offset1:41
	ds_read2st64_b32 v[74:75], v138 offset0:42 offset1:43
	ds_read2st64_b32 v[76:77], v139 offset0:44 offset1:45
	ds_read2st64_b32 v[78:79], v140 offset0:46 offset1:47
	s_waitcnt lgkmcnt(15)
	v_fma_f32 v160, v94, v158, v48
	v_fma_f32 v161, v94, v159, v49
	v_fma_f32 v162, -v95, v159, v160
	v_fma_f32 v163, v95, v158, v161
	s_waitcnt lgkmcnt(14)
	v_fma_f32 v160, v94, v162, v50
	v_fma_f32 v161, v94, v163, v51
	v_fma_f32 v158, -v95, v163, v160
	v_fma_f32 v159, v95, v162, v161
	s_waitcnt lgkmcnt(13)
	v_fma_f32 v160, v94, v158, v52
	v_fma_f32 v161, v94, v159, v53
	v_fma_f32 v162, -v95, v159, v160
	v_fma_f32 v163, v95, v158, v161
	s_waitcnt lgkmcnt(12)
	v_fma_f32 v160, v94, v162, v54
	v_fma_f32 v161, v94, v163, v55
	v_fma_f32 v158, -v95, v163, v160
	v_fma_f32 v159, v95, v162, v161
	s_waitcnt lgkmcnt(11)
	v_fma_f32 v160, v94, v158, v56
	v_fma_f32 v161, v94, v159, v57
	v_fma_f32 v162, -v95, v159, v160
	v_fma_f32 v163, v95, v158, v161
	s_waitcnt lgkmcnt(10)
	v_fma_f32 v160, v94, v162, v58
	v_fma_f32 v161, v94, v163, v59
	v_fma_f32 v158, -v95, v163, v160
	v_fma_f32 v159, v95, v162, v161
	s_waitcnt lgkmcnt(9)
	v_fma_f32 v160, v94, v158, v60
	v_fma_f32 v161, v94, v159, v61
	v_fma_f32 v162, -v95, v159, v160
	v_fma_f32 v163, v95, v158, v161
	s_waitcnt lgkmcnt(8)
	v_fma_f32 v160, v94, v162, v62
	v_fma_f32 v161, v94, v163, v63
	v_fma_f32 v158, -v95, v163, v160
	v_fma_f32 v159, v95, v162, v161
	s_waitcnt lgkmcnt(7)
	v_fma_f32 v160, v94, v158, v64
	v_fma_f32 v161, v94, v159, v65
	v_fma_f32 v162, -v95, v159, v160
	v_fma_f32 v163, v95, v158, v161
	s_waitcnt lgkmcnt(6)
	v_fma_f32 v160, v94, v162, v66
	v_fma_f32 v161, v94, v163, v67
	v_fma_f32 v158, -v95, v163, v160
	v_fma_f32 v159, v95, v162, v161
	s_waitcnt lgkmcnt(5)
	v_fma_f32 v160, v94, v158, v68
	v_fma_f32 v161, v94, v159, v69
	v_fma_f32 v162, -v95, v159, v160
	v_fma_f32 v163, v95, v158, v161
	s_waitcnt lgkmcnt(4)
	v_fma_f32 v160, v94, v162, v70
	v_fma_f32 v161, v94, v163, v71
	v_fma_f32 v158, -v95, v163, v160
	v_fma_f32 v159, v95, v162, v161
	s_waitcnt lgkmcnt(3)
	v_fma_f32 v160, v94, v158, v72
	v_fma_f32 v161, v94, v159, v73
	v_fma_f32 v162, -v95, v159, v160
	v_fma_f32 v163, v95, v158, v161
	s_waitcnt lgkmcnt(2)
	v_fma_f32 v160, v94, v162, v74
	v_fma_f32 v161, v94, v163, v75
	v_fma_f32 v158, -v95, v163, v160
	v_fma_f32 v159, v95, v162, v161
	s_waitcnt lgkmcnt(1)
	v_fma_f32 v160, v94, v158, v76
	v_fma_f32 v161, v94, v159, v77
	v_fma_f32 v162, -v95, v159, v160
	v_fma_f32 v163, v95, v158, v161
	s_waitcnt lgkmcnt(0)
	v_fma_f32 v160, v94, v162, v78
	v_fma_f32 v161, v94, v163, v79
	v_fma_f32 v48, -v95, v163, v160
	v_fma_f32 v49, v95, v162, v161
	s_cbranch_scc0 .LBB0_585
	s_andn2_b64 vcc, exec, s[8:9]
	ds_write_b64 v107, v[48:49]
	s_waitcnt lgkmcnt(0)
	s_barrier
	s_cbranch_vccnz .LBB0_591
	v_pk_mul_f32 v[48:49], v[94:95], v[94:95]
	s_andn2_b64 vcc, exec, s[18:19]
	v_sub_f32_e32 v48, v48, v49
	v_add_f32_e32 v49, v94, v94
	v_mul_f32_e32 v49, v95, v49
	v_mul_f32_e32 v50, v48, v48
	v_add_f32_e32 v48, v48, v48
	v_mul_f32_e32 v48, v49, v48
	v_fma_f32 v50, -v49, v49, v50
	v_mul_f32_e32 v49, v48, v48
	v_fma_f32 v49, v50, v50, -v49
	v_add_f32_e32 v50, v50, v50
	v_mul_f32_e32 v48, v48, v50
	v_mul_f32_e32 v50, v48, v48
	v_fma_f32 v50, v49, v49, -v50
	v_add_f32_e32 v49, v49, v49
	v_mul_f32_e32 v48, v48, v49
	v_mul_f32_e32 v49, v48, v48
	v_fma_f32 v49, v50, v50, -v49
	v_add_f32_e32 v50, v50, v50
	v_mul_f32_e32 v48, v48, v50
	v_mul_f32_e32 v50, v48, v48
	v_fma_f32 v50, v49, v49, -v50
	v_add_f32_e32 v49, v49, v49
	v_mul_f32_e32 v48, v48, v49
	v_mul_f32_e32 v49, v48, v48
	v_fma_f32 v49, v50, v50, -v49
	v_add_f32_e32 v50, v50, v50
	v_mul_f32_e32 v48, v48, v50
	v_mul_f32_e32 v50, v48, v48
	v_fma_f32 v50, v49, v49, -v50
	v_add_f32_e32 v49, v49, v49
	v_mul_f32_e32 v48, v48, v49
	v_mul_f32_e32 v49, v48, v48
	v_fma_f32 v49, v50, v50, -v49
	v_add_f32_e32 v50, v50, v50
	v_mul_f32_e32 v50, v48, v50
	v_mul_f32_e32 v48, v50, v50
	v_fma_f32 v48, v49, v49, -v48
	v_add_f32_e32 v49, v49, v49
	v_mul_f32_e32 v50, v50, v49
	s_cbranch_vccnz .LBB0_592
	v_mov_b32_e32 v76, 0
	v_mov_b32_e32 v49, v48
	v_mov_b32_e32 v51, v50
	s_mov_b32 s15, 0
	v_mov_b32_e32 v52, v108
	v_mov_b32_e32 v77, v76

; #define LAS __attribute__((address_space(3)))
; #define LDS_WAIT() asm volatile("s_waitcnt lgkmcnt(0)" ::: "memory")
; #define MFMA16(a, b, c) __builtin_amdgcn_mfma_f32_16x16x32_bf16(a, b, c, 0, 0, 0)
; __device__ __forceinline__ bf16_t tobf(float x) { return (bf16_t)pk2(x, 0.f); }
; __device__ __forceinline__ void s5_phase(LAS unsigned char* lds, const bf16_t* USSM, const float* S5A, const float* S5B, const float* c_re, const float* c_im, const float* dskip,
;                                          bf16_t* YSSM, int tid, int lane, int wave) {
;     ...
;         for (int tb = 0; tb < 64; ++tb) {
;             bf16x8 a = *(const bf16x8*)(ub + (size_t)(tb * 16 + r16) * 1024 + (q4 & 1) * 8); *(LAS bf16x8*)(UST + r16 * 16 + (q4 & 1) * 8) = a; if (q4 >= 2) a = zf;
; #pragma unroll
;             for (int nt = 0; nt < 8; ++nt) { const f32x4 acc = MFMA16(a, bfr[nt], z4);
; #pragma unroll
;                 for (int i = 0; i < 4; ++i) BU[(q4 * 4 + i) * 132 + nt * 16 + r16] = acc[i]; }
;             LDS_WAIT();
; #pragma unroll
;             for (int t = 0; t < 16; ++t) { const float br = BU[t * 132 + lane], bi = BU[t * 132 + 64 + lane];
;                 const float nr = are * xr - aim * xi + br, ni = are * xi + aim * xr + bi; xr = nr; xi = ni;
;                 XB[t * 136 + lane] = tobf(xr); XB[t * 136 + 64 + lane] = tobf(xi); }
.LBB0_596:
	v_mov_b32_e32 v158, v76
	v_mov_b32_e32 v159, v77
	v_add_u32_e32 v141, v115, v112
	v_add_u32_e32 v146, s6, v82
	v_add_u32_e32 v104, 0x1000, v141
	v_ashrrev_i32_e32 v147, 31, v146
	s_add_i32 s6, s6, 16
	s_cmpk_eq_i32 s6, 0x400
	s_waitcnt vmcnt(4)
	ds_write_b128 v109, v[148:151] offset:16896
	s_nop 0
	v_mfma_f32_16x16x32_bf16 v[56:59], v[148:151], v[0:3], 0
	v_mfma_f32_16x16x32_bf16 v[60:63], v[148:151], v[4:7], 0
	v_mfma_f32_16x16x32_bf16 v[64:67], v[148:151], v[8:11], 0
	v_mfma_f32_16x16x32_bf16 v[68:71], v[148:151], v[16:19], 0
	v_mfma_f32_16x16x32_bf16 v[72:75], v[148:151], v[12:15], 0
	v_mfma_f32_16x16x32_bf16 v[76:79], v[148:151], v[20:23], 0
	v_mfma_f32_16x16x32_bf16 v[142:145], v[148:151], v[24:27], 0
	v_mfma_f32_16x16x32_bf16 v[48:51], v[148:151], v[28:31], 0
	global_load_dwordx4 v[148:151], v[96:97], off
	v_lshl_add_u64 v[96:97], v[96:97], 0, s[56:57]
	s_nop 1
	ds_write2_b32 v124, v56, v60 offset1:16
	ds_write2_b32 v124, v57, v61 offset0:132 offset1:148
	ds_write2_b32 v125, v58, v62 offset0:8 offset1:24
	ds_write2_b32 v125, v59, v63 offset0:140 offset1:156
	ds_write2_b32 v124, v64, v68 offset0:32 offset1:48
	ds_write2_b32 v124, v65, v69 offset0:164 offset1:180
	ds_write2_b32 v125, v66, v70 offset0:40 offset1:56
	ds_write2_b32 v125, v67, v71 offset0:172 offset1:188
	ds_write2_b32 v124, v72, v76 offset0:64 offset1:80
	ds_write2_b32 v124, v73, v77 offset0:196 offset1:212
	ds_write2_b32 v125, v74, v78 offset0:72 offset1:88
	ds_write2_b32 v125, v75, v79 offset0:204 offset1:220
	ds_write2_b32 v124, v142, v48 offset0:96 offset1:112
	ds_write2_b32 v124, v143, v49 offset0:228 offset1:244
	ds_write2_b32 v125, v144, v50 offset0:104 offset1:120
	ds_write2_b32 v125, v145, v51 offset0:236 offset1:252
	s_waitcnt lgkmcnt(0)
	ds_read2st64_b32 v[222:223], v111 offset0:16 offset1:17
	ds_read2st64_b32 v[224:225], v126 offset0:18 offset1:19
	ds_read2st64_b32 v[226:227], v127 offset0:20 offset1:21
	ds_read2st64_b32 v[228:229], v128 offset0:22 offset1:23
	s_waitcnt lgkmcnt(3)
	v_fma_f32 v160, v94, v158, v222
	v_fma_f32 v161, v94, v159, v223
	v_fma_f32 v162, -v95, v159, v160
	v_fma_f32 v163, v95, v158, v161
	ds_read2st64_b32 v[230:231], v129 offset0:24 offset1:25
	v_cvt_pk_bf16_f32 v164, v162, v83
	v_cvt_pk_bf16_f32 v165, v163, v83
	ds_write_b16 v118, v164 offset:12544
	ds_write_b16 v118, v165 offset:12672
	s_waitcnt lgkmcnt(5)
	v_fma_f32 v160, v94, v162, v224
	v_fma_f32 v161, v94, v163, v225
	v_fma_f32 v158, -v95, v163, v160
	v_fma_f32 v159, v95, v162, v161
	ds_read2st64_b32 v[232:233], v130 offset0:26 offset1:27
	v_cvt_pk_bf16_f32 v166, v158, v83
	v_cvt_pk_bf16_f32 v167, v159, v83
	ds_write_b16 v118, v166 offset:12816
	ds_write_b16 v118, v167 offset:12944
	s_waitcnt lgkmcnt(7)
	v_fma_f32 v160, v94, v158, v226
	v_fma_f32 v161, v94, v159, v227
	v_fma_f32 v162, -v95, v159, v160
	v_fma_f32 v163, v95, v158, v161
	ds_read2st64_b32 v[234:235], v131 offset0:28 offset1:29
	v_cvt_pk_bf16_f32 v164, v162, v83
	v_cvt_pk_bf16_f32 v165, v163, v83
	ds_write_b16 v118, v164 offset:13088
	ds_write_b16 v118, v165 offset:13216
	s_waitcnt lgkmcnt(9)
	v_fma_f32 v160, v94, v162, v228
	v_fma_f32 v161, v94, v163, v229
	v_fma_f32 v158, -v95, v163, v160
	v_fma_f32 v159, v95, v162, v161
	ds_read2st64_b32 v[236:237], v132 offset0:30 offset1:31
	v_cvt_pk_bf16_f32 v166, v158, v83
	v_cvt_pk_bf16_f32 v167, v159, v83
	ds_write_b16 v118, v166 offset:13360
	ds_write_b16 v118, v167 offset:13488
	s_waitcnt lgkmcnt(11)
	v_fma_f32 v160, v94, v158, v230
	v_fma_f32 v161, v94, v159, v231
	v_fma_f32 v162, -v95, v159, v160
	v_fma_f32 v163, v95, v158, v161
	ds_read2st64_b32 v[238:239], v133 offset0:32 offset1:33
	v_cvt_pk_bf16_f32 v164, v162, v83
	v_cvt_pk_bf16_f32 v165, v163, v83
	ds_write_b16 v118, v164 offset:13632
	ds_write_b16 v118, v165 offset:13760
	s_waitcnt lgkmcnt(11)
	v_fma_f32 v160, v94, v162, v232
	v_fma_f32 v161, v94, v163, v233
	v_fma_f32 v158, -v95, v163, v160
	v_fma_f32 v159, v95, v162, v161
	ds_read2st64_b32 v[240:241], v134 offset0:34 offset1:35
	v_cvt_pk_bf16_f32 v166, v158, v83
	v_cvt_pk_bf16_f32 v167, v159, v83
	ds_write_b16 v118, v166 offset:13904
	ds_write_b16 v118, v167 offset:14032
	s_waitcnt lgkmcnt(11)
	v_fma_f32 v160, v94, v158, v234
	v_fma_f32 v161, v94, v159, v235
	v_fma_f32 v162, -v95, v159, v160
	v_fma_f32 v163, v95, v158, v161
	ds_read2st64_b32 v[242:243], v135 offset0:36 offset1:37
	v_cvt_pk_bf16_f32 v164, v162, v83
	v_cvt_pk_bf16_f32 v165, v163, v83
	ds_write_b16 v118, v164 offset:14176
	ds_write_b16 v118, v165 offset:14304
	s_waitcnt lgkmcnt(11)
	v_fma_f32 v160, v94, v162, v236
	v_fma_f32 v161, v94, v163, v237
	v_fma_f32 v158, -v95, v163, v160
	v_fma_f32 v159, v95, v162, v161
	ds_read2st64_b32 v[244:245], v136 offset0:38 offset1:39
	v_cvt_pk_bf16_f32 v166, v158, v83
	v_cvt_pk_bf16_f32 v167, v159, v83
	ds_write_b16 v118, v166 offset:14448
	ds_write_b16 v118, v167 offset:14576
	s_waitcnt lgkmcnt(11)
	v_fma_f32 v160, v94, v158, v238
	v_fma_f32 v161, v94, v159, v239
	v_fma_f32 v162, -v95, v159, v160
	v_fma_f32 v163, v95, v158, v161
	ds_read2st64_b32 v[246:247], v137 offset0:40 offset1:41
	v_cvt_pk_bf16_f32 v164, v162, v83
	v_cvt_pk_bf16_f32 v165, v163, v83
	ds_write_b16 v118, v164 offset:14720
	ds_write_b16 v118, v165 offset:14848
	s_waitcnt lgkmcnt(11)
; #define LAS __attribute__((address_space(3)))
; __device__ __forceinline__ unsigned pk2(float lo, float hi) { unsigned r; asm volatile("v_cvt_pk_bf16_f32 %0, %1, %2" : "=v"(r) : "v"(lo), "v"(hi)); return r; }
; __device__ __forceinline__ float gelu_tanh(float x) { return x * sigm(1.5957691216f * (x + 0.044715f * x * x * x)); }
; #define LDS_WAIT() asm volatile("s_waitcnt lgkmcnt(0)" ::: "memory")
; #define MFMA16(a, b, c) __builtin_amdgcn_mfma_f32_16x16x32_bf16(a, b, c, 0, 0, 0)
; __device__ __forceinline__ bf16_t tobf(float x) { return (bf16_t)pk2(x, 0.f); }
; __device__ __forceinline__ void s5_phase(LAS unsigned char* lds, const bf16_t* USSM, const float* S5A, const float* S5B, const float* c_re, const float* c_im, const float* dskip,
;                                          bf16_t* YSSM, int tid, int lane, int wave) {
;     ...
;                 XB[t * 136 + lane] = tobf(xr); XB[t * 136 + 64 + lane] = tobf(xi); }
;             LDS_WAIT();
;             f32x4 y = z4;
; #pragma unroll
;             for (int ks = 0; ks < 4; ++ks) y = MFMA16(*(const LAS bf16x8*)(XB + r16 * 136 + ks * 32 + q4 * 8), cfr[ks], y);
; #pragma unroll
;             for (int i = 0; i < 4; ++i) { const float u = bflo((unsigned)UST[(q4 * 4 + i) * 16 + r16]); BU[(q4 * 4 + i) * 16 + r16] = gelu_tanh(y[i] + dsk * u); }
;             LDS_WAIT();
;             { const f32x4 v = *(const LAS f32x4*)(BU + (lane >> 2) * 16 + (lane & 3) * 4); u32x2 o; o.x = pk2(v[0], v[1]); o.y = pk2(v[2], v[3]);
;               *(u32x2*)(YSSM + ((size_t)(b * SEQ + wave * 1024 + tb * 16 + (lane >> 2))) * 1024 + g * 16 + (lane & 3) * 4) = o; }
;             LDS_WAIT();
;         }
;     }
	v_fma_f32 v160, v94, v162, v240
	v_fma_f32 v161, v94, v163, v241
	v_fma_f32 v158, -v95, v163, v160
	v_fma_f32 v159, v95, v162, v161
	ds_read2st64_b32 v[248:249], v138 offset0:42 offset1:43
	v_cvt_pk_bf16_f32 v166, v158, v83
	v_cvt_pk_bf16_f32 v167, v159, v83
	ds_write_b16 v118, v166 offset:14992
	ds_write_b16 v118, v167 offset:15120
	s_waitcnt lgkmcnt(11)
	v_fma_f32 v160, v94, v158, v242
	v_fma_f32 v161, v94, v159, v243
	v_fma_f32 v162, -v95, v159, v160
	v_fma_f32 v163, v95, v158, v161
	ds_read2st64_b32 v[250:251], v139 offset0:44 offset1:45
	v_cvt_pk_bf16_f32 v164, v162, v83
	v_cvt_pk_bf16_f32 v165, v163, v83
	ds_write_b16 v118, v164 offset:15264
	ds_write_b16 v118, v165 offset:15392
	s_waitcnt lgkmcnt(11)
	v_fma_f32 v160, v94, v162, v244
	v_fma_f32 v161, v94, v163, v245
	v_fma_f32 v158, -v95, v163, v160
	v_fma_f32 v159, v95, v162, v161
	ds_read2st64_b32 v[252:253], v140 offset0:46 offset1:47
	v_cvt_pk_bf16_f32 v166, v158, v83
	v_cvt_pk_bf16_f32 v167, v159, v83
	ds_write_b16 v118, v166 offset:15536
	ds_write_b16 v118, v167 offset:15664
	s_waitcnt lgkmcnt(11)
	v_fma_f32 v160, v94, v158, v246
	v_fma_f32 v161, v94, v159, v247
	v_fma_f32 v162, -v95, v159, v160
	v_fma_f32 v163, v95, v158, v161
	v_cvt_pk_bf16_f32 v164, v162, v83
	v_cvt_pk_bf16_f32 v165, v163, v83
	ds_write_b16 v118, v164 offset:15808
	ds_write_b16 v118, v165 offset:15936
	s_waitcnt lgkmcnt(10)
	v_fma_f32 v160, v94, v162, v248
	v_fma_f32 v161, v94, v163, v249
	v_fma_f32 v158, -v95, v163, v160
	v_fma_f32 v159, v95, v162, v161
	v_cvt_pk_bf16_f32 v166, v158, v83
	v_cvt_pk_bf16_f32 v167, v159, v83
	ds_write_b16 v118, v166 offset:16080
	ds_write_b16 v118, v167 offset:16208
	s_waitcnt lgkmcnt(9)
	v_fma_f32 v160, v94, v158, v250
	v_fma_f32 v161, v94, v159, v251
	v_fma_f32 v162, -v95, v159, v160
	v_fma_f32 v163, v95, v158, v161
	v_cvt_pk_bf16_f32 v164, v162, v83
	v_cvt_pk_bf16_f32 v165, v163, v83
	ds_write_b16 v118, v164 offset:16352
	ds_write_b16 v118, v165 offset:16480
	s_waitcnt lgkmcnt(8)
	v_fma_f32 v160, v94, v162, v252
	v_fma_f32 v161, v94, v163, v253
	v_fma_f32 v76, -v95, v163, v160
	v_fma_f32 v77, v95, v162, v161
	v_cvt_pk_bf16_f32 v166, v76, v83
	v_cvt_pk_bf16_f32 v167, v77, v83
	ds_write_b16 v118, v166 offset:16624
	ds_write_b16 v118, v167 offset:16752
	s_waitcnt lgkmcnt(0)
	ds_read_b128 v[48:51], v119 offset:12544
	ds_read_b128 v[52:55], v119 offset:12608
	ds_read_b128 v[56:59], v119 offset:12672
	s_waitcnt lgkmcnt(2)
	v_mfma_f32_16x16x32_bf16 v[48:51], v[48:51], v[32:35], 0
	ds_read_b128 v[60:63], v119 offset:12736
	ds_read_u16 v64, v113 offset:16896
	ds_read_u16 v65, v115 offset:16928
	s_waitcnt lgkmcnt(4)
	v_mfma_f32_16x16x32_bf16 v[48:51], v[52:55], v[36:39], v[48:51]
	ds_read_u16 v52, v115 offset:16960
	ds_read_u16 v53, v115 offset:16992
	s_waitcnt lgkmcnt(3)
	v_lshlrev_b32_e32 v54, 16, v64
	s_waitcnt lgkmcnt(2)
	v_lshlrev_b32_e32 v55, 16, v65
	v_mfma_f32_16x16x32_bf16 v[48:51], v[56:59], v[40:43], v[48:51]
	s_waitcnt lgkmcnt(1)
	v_lshlrev_b32_e32 v52, 16, v52
	s_waitcnt lgkmcnt(0)
	v_lshlrev_b32_e32 v53, 16, v53
	v_mfma_f32_16x16x32_bf16 v[48:51], v[60:63], v[44:47], v[48:51]
	s_nop 7
	v_fma_f32 v48, v123, v54, v48
	v_fma_f32 v49, v123, v55, v49
	v_fma_f32 v50, v123, v52, v50
	v_fmac_f32_e32 v51, v123, v53
	v_mul_f32_e32 v52, 0x3d372713, v48
	v_mul_f32_e32 v53, 0x3d372713, v49
	v_mul_f32_e32 v54, 0x3d372713, v50
	v_mul_f32_e32 v55, 0x3d372713, v51
	v_mul_f32_e32 v52, v48, v52
	v_mul_f32_e32 v53, v49, v53
	v_mul_f32_e32 v54, v50, v54
	v_mul_f32_e32 v55, v51, v55
	v_fma_f32 v52, v48, v52, v48
	v_fma_f32 v53, v49, v53, v49
	v_fma_f32 v54, v50, v54, v50
	v_fma_f32 v55, v51, v55, v51
	v_mul_f32_e32 v52, 0x3fcc422a, v52
	v_mul_f32_e32 v53, 0x3fcc422a, v53
	v_mul_f32_e32 v54, 0x3fcc422a, v54
	v_mul_f32_e32 v55, 0x3fcc422a, v55
	v_mul_f32_e32 v52, 0xbfb8aa3b, v52
	v_mul_f32_e32 v53, 0xbfb8aa3b, v53
	v_mul_f32_e32 v54, 0xbfb8aa3b, v54
	v_mul_f32_e32 v55, 0xbfb8aa3b, v55
	v_exp_f32_e32 v52, v52
	v_exp_f32_e32 v53, v53
	v_exp_f32_e32 v54, v54
	v_exp_f32_e32 v55, v55
	v_add_f32_e32 v52, 1.0, v52
	v_add_f32_e32 v53, 1.0, v53
	v_add_f32_e32 v54, 1.0, v54
	v_add_f32_e32 v55, 1.0, v55
	v_rcp_f32_e32 v52, v52
	v_rcp_f32_e32 v53, v53
	v_rcp_f32_e32 v54, v54
	v_rcp_f32_e32 v55, v55
	v_mul_f32_e32 v48, v48, v52
	v_mul_f32_e32 v49, v49, v53
	v_mul_f32_e32 v50, v50, v54
	v_mul_f32_e32 v51, v51, v55
	v_lshlrev_b64 v[52:53], 11, v[146:147]
	v_lshl_add_u64 v[52:53], v[100:101], 0, v[52:53]
	v_lshl_add_u64 v[54:55], v[52:53], 0, v[168:169]
	v_lshl_add_u64 v[52:53], v[52:53], 0, v[152:153]
	v_cvt_pk_bf16_f32 v48, v48, v48
	v_cvt_pk_bf16_f32 v49, v49, v49
	v_cvt_pk_bf16_f32 v50, v50, v50
	v_cvt_pk_bf16_f32 v51, v51, v51
	global_store_short v[52:53], v48, off
	global_store_short v[52:53], v49, off offset:2048
	global_store_short v[54:55], v50, off
	global_store_short v[54:55], v51, off offset:2048
	s_waitcnt lgkmcnt(0)
	s_cbranch_scc0 .LBB0_596
	s_add_i32 s43, s43, s84
	s_add_i32 s27, s27, s33
	s_add_i32 s42, s42, s84
	s_cmpk_gt_i32 s43, 0xff
	s_cbranch_scc0 .LBB0_568
